# waitcnt placement: FoX QK^T - all 8 K fragments of the first key half requested up front with counted lgkmcnt waits (was 4 exposed LDS round trips inside the MFMA chain)
# baseline (speedup 1.0000x reference)
; #define LAS __attribute__((address_space(3)))
; __device__ __forceinline__ void qkt(f32x16& p0, f32x16& p1, const LAS char* K_buf, int r32, int hi, const bf16x8* qr) {
;     p0 = f32x16{}; p1 = f32x16{};
;     const LAS char* kb[4];
; #pragma unroll
;     for (int dd = 0; dd < 4; ++dd) kb[dd] = K_buf + KSWZ(r32, (dd * 16 + hi * 8) * 2);
; #pragma unroll
;     for (int d0 = 0; d0 < 8; ++d0) { const LAS char* ap = kb[d0 & 3] + (d0 >> 2) * 128;
;         const bf16x8 b0 = *(const LAS bf16x8*)ap;
;         const bf16x8 b1 = *(const LAS bf16x8*)(ap + 32 * 256);
;         const bf16x8 qf = qr[d0];
;         p0 = __builtin_amdgcn_mfma_f32_32x32x16_bf16(b0, qf, p0, 0, 0, 0);
;         p1 = __builtin_amdgcn_mfma_f32_32x32x16_bf16(b1, qf, p1, 0, 0, 0); }
; }
; template <bool SBK>
; __device__ __forceinline__ void attn_unit(const Args& a, int l, LAS char* lds, int b, int h8, int P0, int orow0, int nvalid) {
;     ...
;                 { const LAS float* cb_ = cm_l + kb + 4 * hi;
; #pragma unroll
;  for (int g = 0; g < 4; ++g) { const f32x4 c0 = *(const LAS f32x4*)(cb_ + 8 * g);
; #pragma unroll
;  for (int e = 0; e < 4; ++e) p0[4 * g + e] -= c0[e]; }
;                   __builtin_amdgcn_sched_barrier(0);
; #pragma unroll
;  for (int g = 0; g < 4; ++g) { const f32x4 c1 = *(const LAS f32x4*)(cb_ + 32 + 8 * g);
; #pragma unroll
;  for (int e = 0; e < 4; ++e) p1[4 * g + e] -= c1[e]; } }
;                 __builtin_amdgcn_sched_barrier(0);
;                 if (needmask) {
; #pragma unroll
;  for (int r = 0; r < 16; ++r) { const int c = (r & 3) + 8 * (r >> 2); if (dq - c < 0) p0[r] = NEG; if (dq - c - 32 < 0) p1[r] = NEG; } }
.LBB0_569:
	s_sub_i32 s5, s7, s23
	s_lshl_b32 s27, s5, 6
	s_cmp_gt_i32 s27, s8
	s_cbranch_scc1 .LBB0_577
	s_lshl_b32 s35, s4, 14
	v_add_u32_e32 v0, s35, v174
	v_add_u32_e32 v14, v0, v176
	v_add_u32_e32 v15, v0, v177
	v_add_u32_e32 v88, v0, v178
	v_add_u32_e32 v0, v0, v179
	ds_read_b128 v[2:5], v14 offset:49152
	ds_read_b128 v[208:211], v15 offset:49152
	ds_read_b128 v[212:215], v88 offset:49152
	ds_read_b128 v[216:219], v0 offset:49152
	ds_read_b128 v[6:9], v14 offset:49280
	ds_read_b128 v[10:13], v15 offset:49280
	ds_read_b128 v[80:83], v88 offset:49280
	ds_read_b128 v[84:87], v0 offset:49280
	ds_read_b128 v[188:191], v88 offset:57344
	ds_read_b128 v[196:199], v0 offset:57344
	ds_read_b128 v[184:187], v15 offset:57472
	ds_read_b128 v[192:195], v88 offset:57472
	ds_read_b128 v[200:203], v0 offset:57472
	s_or_b32 s4, s27, 63
	s_waitcnt lgkmcnt(12)
	v_mfma_f32_32x32x16_bf16 v[96:111], v[2:5], v[112:115], 0
	s_waitcnt lgkmcnt(11)
	v_mfma_f32_32x32x16_bf16 v[96:111], v[208:211], v[116:119], v[96:111]
	s_waitcnt lgkmcnt(10)
	v_mfma_f32_32x32x16_bf16 v[96:111], v[212:215], v[120:123], v[96:111]
	s_waitcnt lgkmcnt(9)
	v_mfma_f32_32x32x16_bf16 v[96:111], v[216:219], v[124:127], v[96:111]
	s_waitcnt lgkmcnt(8)
	v_mfma_f32_32x32x16_bf16 v[96:111], v[6:9], v[128:131], v[96:111]
	s_waitcnt lgkmcnt(7)
	v_mfma_f32_32x32x16_bf16 v[96:111], v[10:13], v[132:135], v[96:111]
	ds_read_b128 v[2:5], v14 offset:57344
	ds_read_b128 v[10:13], v15 offset:57344
	ds_read_b128 v[6:9], v14 offset:57472
	s_waitcnt lgkmcnt(9)
	v_mfma_f32_32x32x16_bf16 v[96:111], v[80:83], v[136:139], v[96:111]
	s_waitcnt lgkmcnt(8)
	v_mfma_f32_32x32x16_bf16 v[96:111], v[84:87], v[140:143], v[96:111]
	s_waitcnt lgkmcnt(2)
	v_mfma_f32_32x32x16_bf16 v[80:95], v[2:5], v[112:115], 0
	v_lshl_add_u32 v0, s27, 2, v180
	s_waitcnt lgkmcnt(1)
	v_mfma_f32_32x32x16_bf16 v[80:95], v[10:13], v[116:119], v[80:95]
	v_mfma_f32_32x32x16_bf16 v[80:95], v[188:191], v[120:123], v[80:95]
	v_mfma_f32_32x32x16_bf16 v[80:95], v[196:199], v[124:127], v[80:95]
	s_waitcnt lgkmcnt(0)
	v_mfma_f32_32x32x16_bf16 v[80:95], v[6:9], v[128:131], v[80:95]
	v_mfma_f32_32x32x16_bf16 v[80:95], v[184:187], v[132:135], v[80:95]
	v_mfma_f32_32x32x16_bf16 v[80:95], v[192:195], v[136:139], v[80:95]
	ds_read_b128 v[184:187], v0
	ds_read_b128 v[188:191], v0 offset:32
	ds_read_b128 v[192:195], v0 offset:64
	ds_read_b128 v[196:199], v0 offset:96
	v_mfma_f32_32x32x16_bf16 v[80:95], v[200:203], v[140:143], v[80:95]
	ds_read_b128 v[2:5], v0 offset:224
	ds_read_b128 v[6:9], v0 offset:192
	ds_read_b128 v[200:203], v0 offset:128
	ds_read_b128 v[204:207], v0 offset:160
	s_waitcnt lgkmcnt(0)
	v_sub_f32_e32 v97, v97, v185
	s_nop 5
	v_sub_f32_e32 v15, v95, v5
	v_sub_f32_e32 v14, v94, v4
	v_sub_f32_e32 v13, v93, v3
	v_sub_f32_e32 v12, v92, v2
	v_sub_f32_e32 v11, v91, v9
	v_sub_f32_e32 v10, v90, v8
	v_sub_f32_e32 v9, v89, v7
	v_sub_f32_e32 v8, v88, v6
	v_sub_f32_e32 v7, v87, v207
	v_sub_f32_e32 v6, v86, v206
	v_sub_f32_e32 v5, v85, v205
	v_sub_f32_e32 v4, v84, v204
	v_sub_f32_e32 v3, v83, v203
	v_sub_f32_e32 v2, v82, v202
	v_sub_f32_e32 v91, v81, v201
	v_sub_f32_e32 v0, v80, v200
	v_sub_f32_e32 v81, v111, v199
	v_sub_f32_e32 v80, v110, v198
	v_sub_f32_e32 v83, v109, v197
	v_sub_f32_e32 v82, v108, v196
	v_sub_f32_e32 v85, v107, v195
	v_sub_f32_e32 v84, v106, v194
	v_sub_f32_e32 v87, v105, v193
	v_sub_f32_e32 v86, v104, v192
	v_sub_f32_e32 v89, v103, v191
	v_sub_f32_e32 v88, v102, v190
	v_sub_f32_e32 v93, v101, v189
	v_sub_f32_e32 v90, v100, v188
	v_sub_f32_e32 v95, v99, v187
	v_sub_f32_e32 v92, v98, v186
	v_sub_f32_e32 v94, v96, v184
	s_cmp_le_i32 s4, s31
	s_cbranch_scc1 .LBB0_572
	v_or_b32_e32 v96, s27, v172
	v_sub_u32_e32 v98, v155, v96
	v_cmp_lt_i32_e32 vcc, -1, v98
	v_xad_u32 v96, v96, -1, v155
	s_nop 0
	v_cndmask_b32_e32 v94, v245, v94, vcc
	v_cmp_lt_i32_e32 vcc, 31, v98
	s_nop 1
	v_cndmask_b32_e32 v0, v245, v0, vcc
	v_cmp_lt_i32_e32 vcc, -1, v96
	s_nop 1
	v_cndmask_b32_e32 v97, v245, v97, vcc
	v_cmp_lt_i32_e32 vcc, 31, v96
	v_or_b32_e32 v96, s27, v170
	v_sub_u32_e32 v96, v155, v96
	v_cndmask_b32_e32 v91, v245, v91, vcc
	v_cmp_lt_i32_e32 vcc, -1, v96
	s_nop 1
	v_cndmask_b32_e32 v92, v245, v92, vcc
	v_cmp_lt_i32_e32 vcc, 31, v96
	v_or_b32_e32 v96, s27, v169
	v_sub_u32_e32 v96, v155, v96
	v_cndmask_b32_e32 v2, v245, v2, vcc
	v_cmp_lt_i32_e32 vcc, -1, v96
	s_nop 1
	v_cndmask_b32_e32 v95, v245, v95, vcc
	v_cmp_lt_i32_e32 vcc, 31, v96
	v_or_b32_e32 v96, s27, v168
	v_sub_u32_e32 v96, v155, v96
	v_cndmask_b32_e32 v3, v245, v3, vcc
	v_cmp_lt_i32_e32 vcc, -1, v96
	s_nop 1
	v_cndmask_b32_e32 v90, v245, v90, vcc
	v_cmp_lt_i32_e32 vcc, 31, v96
	v_or_b32_e32 v96, s27, v167
	v_sub_u32_e32 v96, v155, v96
	v_cndmask_b32_e32 v4, v245, v4, vcc
	v_cmp_lt_i32_e32 vcc, -1, v96
	s_nop 1
	v_cndmask_b32_e32 v93, v245, v93, vcc
	v_cmp_lt_i32_e32 vcc, 31, v96
	v_or_b32_e32 v96, s27, v165
	v_sub_u32_e32 v96, v155, v96
	v_cndmask_b32_e32 v5, v245, v5, vcc
	v_cmp_lt_i32_e32 vcc, -1, v96
	s_nop 1
	v_cndmask_b32_e32 v88, v245, v88, vcc
	v_cmp_lt_i32_e32 vcc, 31, v96
	v_or_b32_e32 v96, s27, v164
	v_sub_u32_e32 v96, v155, v96
	v_cndmask_b32_e32 v6, v245, v6, vcc
	v_cmp_lt_i32_e32 vcc, -1, v96
	s_nop 1
	v_cndmask_b32_e32 v89, v245, v89, vcc
	v_cmp_lt_i32_e32 vcc, 31, v96
	v_or_b32_e32 v96, s27, v163
	v_sub_u32_e32 v96, v155, v96
	v_cndmask_b32_e32 v7, v245, v7, vcc
	v_cmp_lt_i32_e32 vcc, -1, v96
	s_nop 1
	v_cndmask_b32_e32 v86, v245, v86, vcc
	v_cmp_lt_i32_e32 vcc, 31, v96
	v_or_b32_e32 v96, s27, v162
	v_sub_u32_e32 v96, v155, v96
	v_cndmask_b32_e32 v8, v245, v8, vcc
	v_cmp_lt_i32_e32 vcc, -1, v96
	s_nop 1
	v_cndmask_b32_e32 v87, v245, v87, vcc
	v_cmp_lt_i32_e32 vcc, 31, v96
	v_or_b32_e32 v96, s27, v161
	v_sub_u32_e32 v96, v155, v96
	v_cndmask_b32_e32 v9, v245, v9, vcc
	v_cmp_lt_i32_e32 vcc, -1, v96
	s_nop 1
	v_cndmask_b32_e32 v84, v245, v84, vcc
	v_cmp_lt_i32_e32 vcc, 31, v96
	v_or_b32_e32 v96, s27, v160
	v_sub_u32_e32 v96, v155, v96
	v_cndmask_b32_e32 v10, v245, v10, vcc
	v_cmp_lt_i32_e32 vcc, -1, v96
	s_nop 1
	v_cndmask_b32_e32 v85, v245, v85, vcc
	v_cmp_lt_i32_e32 vcc, 31, v96
	v_or_b32_e32 v96, s27, v159
	v_sub_u32_e32 v96, v155, v96
	v_cndmask_b32_e32 v11, v245, v11, vcc
	v_cmp_lt_i32_e32 vcc, -1, v96
	s_nop 1
	v_cndmask_b32_e32 v82, v245, v82, vcc
	v_cmp_lt_i32_e32 vcc, 31, v96
	v_or_b32_e32 v96, s27, v158
	v_sub_u32_e32 v96, v155, v96
	v_cndmask_b32_e32 v12, v245, v12, vcc
	v_cmp_lt_i32_e32 vcc, -1, v96
	s_nop 1
	v_cndmask_b32_e32 v83, v245, v83, vcc
	v_cmp_lt_i32_e32 vcc, 31, v96
	v_or_b32_e32 v96, s27, v157
	v_sub_u32_e32 v96, v155, v96
	v_cndmask_b32_e32 v13, v245, v13, vcc
	v_cmp_lt_i32_e32 vcc, -1, v96
	s_nop 1
	v_cndmask_b32_e32 v80, v245, v80, vcc
	v_cmp_lt_i32_e32 vcc, 31, v96
	v_or_b32_e32 v96, s27, v156
	v_sub_u32_e32 v96, v155, v96
	v_cndmask_b32_e32 v14, v245, v14, vcc
	v_cmp_lt_i32_e32 vcc, -1, v96
	s_nop 1
	v_cndmask_b32_e32 v81, v245, v81, vcc
	v_cmp_lt_i32_e32 vcc, 31, v96
	s_nop 1
	v_cndmask_b32_e32 v15, v245, v15, vcc
